# NA bias block rewrite: padded stride-32 bias table (masked lanes read -1e30), no readlane masks
# speedup vs baseline: 1.0611x; 1.0050x over previous
.LBB0_241:
	s_cmp_lt_i32 s24, 1
	s_mov_b32 s26, 0
	s_cbranch_scc1 .LBB0_289
	v_and_b32_e32 v23, 12, v2
	v_lshrrev_b32_e64 v23, v23, s57
	v_xor_b32_e32 v0, v23, v0
	v_ashrrev_i32_e32 v2, 7, v2
	v_lshlrev_b32_e32 v22, 6, v3
	v_lshlrev_b32_e32 v0, 4, v0
	v_add_u32_e32 v2, s14, v2
	v_and_or_b32 v0, v0, 48, v22
	v_max_i32_e32 v22, 4, v2
	v_add_u32_e32 v22, -4, v22
	v_and_b32_e32 v20, 32, v20
	v_min_u32_e32 v166, 0x78, v22
	v_or_b32_e32 v22, v20, v3
	v_lshlrev_b32_e32 v21, 3, v21
	v_sub_u32_e64 v23, v22, 8 clamp
	v_cmp_ge_u32_e64 s[0:1], v21, v23
	v_add_u32_e32 v24, 16, v23
	v_or_b32_e32 v25, 2, v21
	v_writelane_b32 v224, s0, 26
	v_or_b32_e32 v26, 1, v21
	v_or_b32_e32 v27, 3, v21
	v_writelane_b32 v224, s1, 27
	v_cmp_lt_u32_e64 s[0:1], v21, v24
	v_or_b32_e32 v28, 4, v21
	v_or_b32_e32 v29, 6, v21
	v_writelane_b32 v224, s0, 28
	v_or_b32_e32 v30, 5, v21
	v_or_b32_e32 v31, 7, v21
	v_writelane_b32 v224, s1, 29
	v_cmp_lt_u32_e64 s[0:1], v25, v23
	v_or_b32_e32 v32, 32, v21
	v_or_b32_e32 v33, 34, v21
	v_writelane_b32 v224, s0, 30
	v_or_b32_e32 v34, 33, v21
	v_or_b32_e32 v35, 35, v21
	v_writelane_b32 v224, s1, 31
	v_cmp_lt_u32_e64 s[0:1], v26, v23
	v_or_b32_e32 v36, 36, v21
	v_or_b32_e32 v37, 38, v21
	v_writelane_b32 v224, s0, 32
	v_or_b32_e32 v38, 37, v21
	v_min_u32_e32 v22, 40, v22
	v_writelane_b32 v224, s1, 33
	v_cmp_lt_u32_e64 s[0:1], v25, v24
	v_add_u32_e32 v168, 0, v0
	v_sub_u32_e32 v0, v21, v3
	v_writelane_b32 v224, s0, 34
	s_mul_i32 s2, s21, 0x7c
	v_sub_u32_e32 v0, v0, v20
	v_writelane_b32 v224, s1, 35
	v_cmp_lt_u32_e64 s[0:1], v26, v24
	v_max_i32_e32 v3, -16, v0
	v_add_u32_e32 v3, 16, v3
	v_writelane_b32 v224, s0, 36
	v_min_u32_e32 v3, 30, v3
	v_lshlrev_b32_e32 v169, 2, v3
	v_writelane_b32 v224, s1, 37
	v_cmp_lt_u32_e64 s[0:1], v27, v23
	v_mov_b32_e32 v219, 0
	v_add_u32_e32 v167, 8, v166
	v_writelane_b32 v224, s0, 38
	s_mov_b32 s27, 2
	s_sub_i32 s14, 0, s25
	v_writelane_b32 v224, s1, 39
	v_cmp_lt_u32_e64 s[0:1], v27, v24
	v_mov_b32_e32 v220, 0
	s_mov_b32 s12, 0
	v_writelane_b32 v224, s0, 40
	v_mov_b32_e32 v56, 0
	v_mov_b32_e32 v57, v219
	v_writelane_b32 v224, s1, 41
	v_cmp_ge_u32_e64 s[0:1], v28, v23
	v_mov_b32_e32 v58, v219
	v_mov_b32_e32 v59, v219
	v_writelane_b32 v224, s0, 42
	v_mov_b32_e32 v39, v219
	s_nop 0
	v_writelane_b32 v224, s1, 43
	v_cmp_lt_u32_e64 s[0:1], v28, v24
	s_nop 1
	v_writelane_b32 v224, s0, 44
	s_nop 1
	v_writelane_b32 v224, s1, 45
	v_cmp_lt_u32_e64 s[0:1], v29, v23
	s_nop 1
	v_writelane_b32 v224, s0, 46
	s_nop 1
	v_writelane_b32 v224, s1, 47
	v_cmp_lt_u32_e64 s[0:1], v30, v23
	s_nop 1
	v_writelane_b32 v224, s0, 48
	s_nop 1
	v_writelane_b32 v224, s1, 49
	v_cmp_lt_u32_e64 s[0:1], v29, v24
	s_nop 1
	v_writelane_b32 v224, s0, 50
	s_nop 1
	v_writelane_b32 v224, s1, 51
	v_cmp_lt_u32_e64 s[0:1], v30, v24
	s_nop 1
	v_writelane_b32 v224, s0, 52
	s_nop 1
	v_writelane_b32 v224, s1, 53
	v_cmp_lt_u32_e64 s[0:1], v31, v23
	s_nop 1
	v_writelane_b32 v224, s0, 54
	s_nop 1
	v_writelane_b32 v224, s1, 55
	v_cmp_lt_u32_e64 s[0:1], v31, v24
	s_nop 1
	v_writelane_b32 v224, s0, 56
	s_nop 1
	v_writelane_b32 v224, s1, 57
	v_cmp_ge_u32_e64 s[0:1], v32, v23
	s_nop 1
	v_writelane_b32 v224, s0, 58
	s_nop 1
	v_writelane_b32 v224, s1, 59
	v_cmp_lt_u32_e64 s[0:1], v32, v24
	s_nop 1
	v_writelane_b32 v224, s0, 60
	s_nop 1
	v_writelane_b32 v224, s1, 61
	v_cmp_lt_u32_e64 s[0:1], v33, v23
	s_nop 1
	v_writelane_b32 v224, s0, 62
	s_nop 1
	v_writelane_b32 v224, s1, 63
	v_cmp_lt_u32_e64 s[0:1], v34, v23
	s_nop 1
	v_writelane_b32 v221, s0, 0
	s_nop 1
	v_writelane_b32 v221, s1, 1
	v_cmp_lt_u32_e64 s[0:1], v33, v24
	s_nop 1
	v_writelane_b32 v221, s0, 2
	s_nop 1
	v_writelane_b32 v221, s1, 3
	v_cmp_lt_u32_e64 s[0:1], v34, v24
	s_nop 1
	v_writelane_b32 v221, s0, 4
	s_nop 1
	v_writelane_b32 v221, s1, 5
	v_cmp_lt_u32_e64 s[0:1], v35, v23
	s_nop 1
	v_writelane_b32 v221, s0, 6
	s_nop 1
	v_writelane_b32 v221, s1, 7
	v_cmp_lt_u32_e64 s[0:1], v35, v24
	s_nop 1
	v_writelane_b32 v221, s0, 8
	s_nop 1
	v_writelane_b32 v221, s1, 9
	v_cmp_ge_u32_e64 s[0:1], v36, v23
	s_nop 1
	v_writelane_b32 v221, s0, 10
	s_nop 1
	v_writelane_b32 v221, s1, 11
	v_cmp_lt_u32_e64 s[0:1], v36, v24
	s_nop 1
	v_writelane_b32 v221, s0, 12
	s_nop 1
	v_writelane_b32 v221, s1, 13
	v_cmp_lt_u32_e64 s[0:1], v37, v23
	s_nop 1
	v_writelane_b32 v221, s0, 14
	s_nop 1
	v_writelane_b32 v221, s1, 15
	v_cmp_lt_u32_e64 s[0:1], v38, v23
	v_or_b32_e32 v23, 39, v21
	s_nop 0
	v_writelane_b32 v221, s0, 16
	s_nop 1
	v_writelane_b32 v221, s1, 17
	v_cmp_lt_u32_e64 s[0:1], v37, v24
	s_nop 1
	v_writelane_b32 v221, s0, 18
	s_nop 1
	v_writelane_b32 v221, s1, 19
	v_cmp_lt_u32_e64 s[0:1], v38, v24
	s_nop 1
	v_writelane_b32 v221, s0, 20
	s_nop 1
	v_writelane_b32 v221, s1, 21
	v_cmp_lt_u32_e64 s[0:1], v23, v24
	v_add_u32_e32 v24, 8, v22
	v_add_u32_e32 v22, 24, v22
	v_writelane_b32 v221, s0, 22
	v_cmp_lt_u32_e64 s[6:7], v32, v22
	v_cmp_lt_u32_e64 s[8:9], v36, v22
	v_writelane_b32 v221, s1, 23
	v_cmp_ge_u32_e64 s[0:1], v21, v24
	v_cmp_lt_u32_e64 s[16:17], v30, v22
	v_cmp_lt_u32_e64 s[18:19], v31, v24
	v_writelane_b32 v221, s0, 24
	v_cmp_lt_u32_e64 s[36:37], v31, v22
	v_cmp_lt_u32_e64 s[56:57], v33, v24
	v_writelane_b32 v221, s1, 25
	v_cmp_lt_u32_e64 s[0:1], v21, v22
	v_cmp_lt_u32_e64 s[76:77], v34, v24
	v_cmp_lt_u32_e64 s[88:89], v33, v22
	v_writelane_b32 v221, s0, 26
	v_cmp_lt_u32_e64 s[22:23], v35, v24
	v_cmp_lt_u32_e64 s[40:41], v35, v22
	v_writelane_b32 v221, s1, 27
	v_cmp_lt_u32_e64 s[0:1], v25, v24
	v_cmp_ge_u32_e64 s[38:39], v36, v24
	v_cmp_lt_u32_e64 s[42:43], v37, v24
	v_writelane_b32 v221, s0, 28
	v_cmp_lt_u32_e64 s[44:45], v38, v24
	v_cmp_lt_u32_e64 s[46:47], v37, v22
	v_writelane_b32 v221, s1, 29
	v_cmp_lt_u32_e64 s[0:1], v26, v24
	v_cmp_lt_u32_e64 s[48:49], v38, v22
	v_cmp_lt_u32_e64 s[50:51], v23, v24
	v_writelane_b32 v221, s0, 30
	v_cmp_lt_u32_e64 s[52:53], v23, v22
	v_mov_b32_e32 v36, v219
	v_writelane_b32 v221, s1, 31
	v_cmp_lt_u32_e64 s[0:1], v25, v22
	v_mov_b32_e32 v37, v219
	v_mov_b32_e32 v38, v219
	v_writelane_b32 v221, s0, 32
	s_nop 1
	v_writelane_b32 v221, s1, 33
	v_cmp_lt_u32_e64 s[0:1], v26, v22
	s_nop 1
	v_writelane_b32 v221, s0, 34
	s_nop 1
	v_writelane_b32 v221, s1, 35
	v_cmp_lt_u32_e64 s[0:1], v27, v24
	s_nop 1
	v_writelane_b32 v221, s0, 36
	s_nop 1
	v_writelane_b32 v221, s1, 37
	v_cmp_lt_u32_e64 s[0:1], v27, v22
	s_nop 1
	v_writelane_b32 v221, s0, 38
	s_nop 1
	v_writelane_b32 v221, s1, 39
	v_cmp_ge_u32_e64 s[0:1], v28, v24
	s_nop 1
	v_writelane_b32 v221, s0, 40
	s_nop 1
	v_writelane_b32 v221, s1, 41
	v_cmp_lt_u32_e64 s[0:1], v28, v22
	s_nop 1
	v_writelane_b32 v221, s0, 42
	s_nop 1
	v_writelane_b32 v221, s1, 43
	v_cmp_lt_u32_e64 s[0:1], v29, v24
	s_nop 1
	v_writelane_b32 v221, s0, 44
	s_nop 1
	v_writelane_b32 v221, s1, 45
	v_cmp_lt_u32_e64 s[0:1], v30, v24
	s_nop 1
	v_writelane_b32 v221, s0, 46
	s_nop 1
	v_writelane_b32 v221, s1, 47
	v_cmp_lt_u32_e64 s[0:1], v29, v22
	s_nop 1
	v_writelane_b32 v221, s0, 48
	s_nop 1
	v_writelane_b32 v221, s1, 49
	v_writelane_b32 v221, s6, 50
	v_cmp_ge_u32_e64 s[0:1], v32, v24
	s_nop 0
	v_writelane_b32 v221, s7, 51
	v_writelane_b32 v221, s8, 52
	v_cmp_lt_u32_e64 s[6:7], v34, v22
	s_nop 0
	v_writelane_b32 v221, s9, 53
	s_movk_i32 s8, 0x7c
	v_mul_lo_u32 v2, v2, s8
	v_sub_u32_e32 v2, s2, v2
	v_add_u32_e32 v170, 0, v2
	v_max_i32_e32 v2, 0xffffffef, v0
	v_add_u32_e32 v2, 17, v2
	v_min_u32_e32 v2, 30, v2
	v_lshlrev_b32_e32 v171, 2, v2
	v_max_i32_e32 v2, 0xffffffee, v0
	v_add_u32_e32 v2, 18, v2
	v_min_u32_e32 v2, 30, v2
	v_lshlrev_b32_e32 v172, 2, v2
	v_max_i32_e32 v2, -15, v0
	v_add_u32_e32 v2, 15, v2
	v_min_u32_e32 v2, 30, v2
	v_lshlrev_b32_e32 v173, 2, v2
	v_add_u32_e32 v2, 4, v0
	v_max_i32_e32 v3, -16, v2
	v_add_u32_e32 v3, 16, v3
	v_min_u32_e32 v3, 30, v3
	v_lshlrev_b32_e32 v174, 2, v3
	v_max_i32_e32 v3, 0xffffffef, v2
	v_add_u32_e32 v3, 17, v3
	v_min_u32_e32 v3, 30, v3
	v_lshlrev_b32_e32 v175, 2, v3
	v_max_i32_e32 v3, 0xffffffee, v2
	v_max_i32_e32 v2, -15, v2
	v_add_u32_e32 v2, 15, v2
	v_min_u32_e32 v2, 30, v2
	v_lshlrev_b32_e32 v177, 2, v2
	v_add_u32_e32 v2, 48, v0
	v_min_u32_e32 v2, 30, v2
	v_lshlrev_b32_e32 v178, 2, v2
	v_add_u32_e32 v2, 49, v0
	v_min_u32_e32 v2, 30, v2
	v_lshlrev_b32_e32 v179, 2, v2
	v_add_u32_e32 v2, 50, v0
	v_min_u32_e32 v2, 30, v2
	v_lshlrev_b32_e32 v180, 2, v2
	v_add_u32_e32 v2, 47, v0
	v_min_u32_e32 v2, 30, v2
	v_lshlrev_b32_e32 v181, 2, v2
	v_add_u32_e32 v2, 52, v0
	v_min_u32_e32 v2, 30, v2
	v_lshlrev_b32_e32 v182, 2, v2
	v_add_u32_e32 v2, 53, v0
	v_min_u32_e32 v2, 30, v2
	v_lshlrev_b32_e32 v183, 2, v2
	v_add_u32_e32 v2, 54, v0
	v_min_u32_e32 v2, 30, v2
	v_lshlrev_b32_e32 v184, 2, v2
	v_add_u32_e32 v2, 51, v0
	v_add_u32_e32 v3, 18, v3
	v_min_u32_e32 v2, 30, v2
	v_min_u32_e32 v3, 30, v3
	v_lshlrev_b32_e32 v185, 2, v2
	v_add_u32_e32 v2, -16, v0
	v_lshlrev_b32_e32 v176, 2, v3
	v_max_i32_e32 v3, -16, v2
	v_lshlrev_b32_e32 v186, 2, v3
	v_max_i32_e32 v3, 0xffffffef, v2
	v_lshlrev_b32_e32 v187, 2, v3
	v_max_i32_e32 v3, 0xffffffee, v2
	v_max_i32_e32 v2, -15, v2
	v_lshlrev_b32_e32 v189, 2, v2
	v_add_u32_e32 v2, -12, v0
	v_lshlrev_b32_e32 v188, 2, v3
	v_max_i32_e32 v3, -16, v2
	v_add_u32_e32 v3, 16, v3
	v_min_u32_e32 v3, 30, v3
	v_lshlrev_b32_e32 v190, 2, v3
	v_max_i32_e32 v3, 0xffffffef, v2
	v_add_u32_e32 v3, 17, v3
	v_min_u32_e32 v3, 30, v3
	v_lshlrev_b32_e32 v191, 2, v3
	v_max_i32_e32 v3, 0xffffffee, v2
	v_add_u32_e32 v3, 18, v3
	v_max_i32_e32 v2, -15, v2
	v_min_u32_e32 v3, 30, v3
	v_lshlrev_b32_e32 v193, 2, v2
	v_add_u32_e32 v2, 16, v0
	v_lshlrev_b32_e32 v192, 2, v3
	v_max_i32_e32 v3, -16, v2
	v_add_u32_e32 v3, 16, v3
	v_min_u32_e32 v3, 30, v3
	v_lshlrev_b32_e32 v194, 2, v3
	v_max_i32_e32 v3, 0xffffffef, v2
	v_add_u32_e32 v3, 17, v3
	v_min_u32_e32 v3, 30, v3
	v_lshlrev_b32_e32 v195, 2, v3
	v_max_i32_e32 v3, 0xffffffee, v2
	v_max_i32_e32 v2, -15, v2
	v_add_u32_e32 v2, 15, v2
	v_min_u32_e32 v2, 30, v2
	v_add_u32_e32 v0, 20, v0
	v_lshlrev_b32_e32 v214, 2, v2
	v_max_i32_e32 v2, -16, v0
	v_add_u32_e32 v2, 16, v2
	v_min_u32_e32 v2, 30, v2
	v_lshlrev_b32_e32 v215, 2, v2
	v_max_i32_e32 v2, 0xffffffef, v0
	v_add_u32_e32 v2, 17, v2
	v_min_u32_e32 v2, 30, v2
	v_lshlrev_b32_e32 v216, 2, v2
	v_max_i32_e32 v2, 0xffffffee, v0
	v_add_u32_e32 v3, 18, v3
	v_add_u32_e32 v2, 18, v2
	v_max_i32_e32 v0, -15, v0
	v_min_u32_e32 v3, 30, v3
	v_min_u32_e32 v2, 30, v2
	v_add_u32_e32 v0, 15, v0
	v_lshlrev_b32_e32 v213, 2, v3
	v_lshlrev_b32_e32 v217, 2, v2
	v_min_u32_e32 v0, 30, v0
	v_mov_b32_e32 v2, v1
	v_mov_b32_e32 v3, v1
	v_lshlrev_b32_e32 v218, 2, v0
	v_mov_b32_e32 v0, v1
	v_mov_b64_e32 v[54:55], v[2:3]
	v_mov_b64_e32 v[34:35], v[2:3]
	v_mov_b64_e32 v[50:51], v[2:3]
	v_mov_b64_e32 v[30:31], v[2:3]
	v_mov_b64_e32 v[46:47], v[2:3]
	v_mov_b64_e32 v[26:27], v[2:3]
	v_mov_b64_e32 v[42:43], v[2:3]
	v_mov_b64_e32 v[22:23], v[2:3]
	s_mov_b64 s[8:9], -1
	v_mov_b64_e32 v[52:53], v[0:1]
	v_mov_b64_e32 v[32:33], v[0:1]
	v_mov_b64_e32 v[48:49], v[0:1]
	v_mov_b64_e32 v[28:29], v[0:1]
	v_mov_b64_e32 v[44:45], v[0:1]
	v_mov_b64_e32 v[24:25], v[0:1]
	v_mov_b64_e32 v[40:41], v[0:1]
	v_mov_b64_e32 v[20:21], v[0:1]
	v_readlane_b32 vcc_lo, v225, 56
	v_readlane_b32 s100, v225, 16
	v_readlane_b32 s101, v225, 17
	s_nop 3
	s_cmp_ge_u32 vcc_lo, 12
	s_cselect_b32 vcc_lo, 8, 0
	s_and_b32 vcc_hi, s20, 7
	s_add_i32 vcc_lo, vcc_lo, vcc_hi
	s_mulk_i32 vcc_lo, 0x744
	s_add_u32 s100, s100, vcc_lo
	s_addc_u32 s101, s101, 0
	v_and_b32_e32 v124, 31, v196
	v_lshrrev_b32_e32 v125, 5, v196
	v_mul_u32_u24_e32 v126, 31, v125
	v_add_u32_e32 v126, v126, v124
	v_lshlrev_b32_e32 v126, 2, v126
	v_add_u32_e32 v128, 0x3e0, v126
	v_min_u32_e32 v126, 0x740, v126
	v_min_u32_e32 v128, 0x740, v128
	global_load_dword v127, v126, s[100:101]
	global_load_dword v129, v128, s[100:101]
	v_and_b32_e32 v130, 15, v196
	v_bfe_u32 v131, v196, 4, 2
	v_lshrrev_b32_e32 v132, 6, v196
	v_and_b32_e32 v133, 1, v132
	v_lshl_add_u32 v133, v133, 5, v130
	v_lshlrev_b32_e32 v131, 3, v131
	s_bfe_u32 vcc_lo, s20, 0x60003
	s_lshl_b32 vcc_lo, vcc_lo, 1
	v_lshrrev_b32_e32 v218, 1, v132
	v_add_u32_e32 v218, vcc_lo, v218
	v_mov_b32_e32 v137, 0x7c
	v_add_u32_e32 v134, -8, v133
	v_max_i32_e32 v134, 0, v134
	v_min_i32_e32 v134, 48, v134
	v_add_u32_e32 v135, 0, v131
	v_sub_u32_e32 v136, v135, v134
	v_cmp_gt_u32_e32 vcc, 16, v136
	v_sub_u32_e32 v135, v135, v133
	v_add_u32_e32 v135, 15, v135
	v_lshlrev_b32_e32 v135, 2, v135
	v_cndmask_b32_e32 v169, v137, v135, vcc
	v_add_u32_e32 v135, 1, v131
	v_sub_u32_e32 v136, v135, v134
	v_cmp_gt_u32_e32 vcc, 16, v136
	v_sub_u32_e32 v135, v135, v133
	v_add_u32_e32 v135, 15, v135
	v_lshlrev_b32_e32 v135, 2, v135
	v_cndmask_b32_e32 v171, v137, v135, vcc
	v_add_u32_e32 v135, 2, v131
	v_sub_u32_e32 v136, v135, v134
	v_cmp_gt_u32_e32 vcc, 16, v136
	v_sub_u32_e32 v135, v135, v133
	v_add_u32_e32 v135, 15, v135
	v_lshlrev_b32_e32 v135, 2, v135
	v_cndmask_b32_e32 v172, v137, v135, vcc
	v_add_u32_e32 v135, 3, v131
	v_sub_u32_e32 v136, v135, v134
	v_cmp_gt_u32_e32 vcc, 16, v136
	v_sub_u32_e32 v135, v135, v133
	v_add_u32_e32 v135, 15, v135
	v_lshlrev_b32_e32 v135, 2, v135
	v_cndmask_b32_e32 v173, v137, v135, vcc
	v_add_u32_e32 v135, 4, v131
	v_sub_u32_e32 v136, v135, v134
	v_cmp_gt_u32_e32 vcc, 16, v136
	v_sub_u32_e32 v135, v135, v133
	v_add_u32_e32 v135, 15, v135
	v_lshlrev_b32_e32 v135, 2, v135
	v_cndmask_b32_e32 v174, v137, v135, vcc
	v_add_u32_e32 v135, 5, v131
	v_sub_u32_e32 v136, v135, v134
	v_cmp_gt_u32_e32 vcc, 16, v136
	v_sub_u32_e32 v135, v135, v133
	v_add_u32_e32 v135, 15, v135
	v_lshlrev_b32_e32 v135, 2, v135
	v_cndmask_b32_e32 v175, v137, v135, vcc
	v_add_u32_e32 v135, 6, v131
	v_sub_u32_e32 v136, v135, v134
	v_cmp_gt_u32_e32 vcc, 16, v136
	v_sub_u32_e32 v135, v135, v133
	v_add_u32_e32 v135, 15, v135
	v_lshlrev_b32_e32 v135, 2, v135
	v_cndmask_b32_e32 v176, v137, v135, vcc
	v_add_u32_e32 v135, 7, v131
	v_sub_u32_e32 v136, v135, v134
	v_cmp_gt_u32_e32 vcc, 16, v136
	v_sub_u32_e32 v135, v135, v133
	v_add_u32_e32 v135, 15, v135
	v_lshlrev_b32_e32 v135, 2, v135
	v_cndmask_b32_e32 v177, v137, v135, vcc
	v_add_u32_e32 v135, 32, v131
	v_sub_u32_e32 v136, v135, v134
	v_cmp_gt_u32_e32 vcc, 16, v136
	v_sub_u32_e32 v135, v135, v133
	v_add_u32_e32 v135, 15, v135
	v_lshlrev_b32_e32 v135, 2, v135
	v_cndmask_b32_e32 v178, v137, v135, vcc
	v_add_u32_e32 v135, 33, v131
	v_sub_u32_e32 v136, v135, v134
	v_cmp_gt_u32_e32 vcc, 16, v136
	v_sub_u32_e32 v135, v135, v133
	v_add_u32_e32 v135, 15, v135
	v_lshlrev_b32_e32 v135, 2, v135
	v_cndmask_b32_e32 v179, v137, v135, vcc
	v_add_u32_e32 v135, 34, v131
	v_sub_u32_e32 v136, v135, v134
	v_cmp_gt_u32_e32 vcc, 16, v136
	v_sub_u32_e32 v135, v135, v133
	v_add_u32_e32 v135, 15, v135
	v_lshlrev_b32_e32 v135, 2, v135
	v_cndmask_b32_e32 v180, v137, v135, vcc
	v_add_u32_e32 v135, 35, v131
	v_sub_u32_e32 v136, v135, v134
	v_cmp_gt_u32_e32 vcc, 16, v136
	v_sub_u32_e32 v135, v135, v133
	v_add_u32_e32 v135, 15, v135
	v_lshlrev_b32_e32 v135, 2, v135
	v_cndmask_b32_e32 v181, v137, v135, vcc
	v_add_u32_e32 v135, 36, v131
	v_sub_u32_e32 v136, v135, v134
	v_cmp_gt_u32_e32 vcc, 16, v136
	v_sub_u32_e32 v135, v135, v133
	v_add_u32_e32 v135, 15, v135
	v_lshlrev_b32_e32 v135, 2, v135
	v_cndmask_b32_e32 v182, v137, v135, vcc
	v_add_u32_e32 v135, 37, v131
	v_sub_u32_e32 v136, v135, v134
	v_cmp_gt_u32_e32 vcc, 16, v136
	v_sub_u32_e32 v135, v135, v133
	v_add_u32_e32 v135, 15, v135
	v_lshlrev_b32_e32 v135, 2, v135
	v_cndmask_b32_e32 v183, v137, v135, vcc
	v_add_u32_e32 v135, 38, v131
	v_sub_u32_e32 v136, v135, v134
	v_cmp_gt_u32_e32 vcc, 16, v136
	v_sub_u32_e32 v135, v135, v133
	v_add_u32_e32 v135, 15, v135
	v_lshlrev_b32_e32 v135, 2, v135
	v_cndmask_b32_e32 v184, v137, v135, vcc
	v_add_u32_e32 v135, 39, v131
	v_sub_u32_e32 v136, v135, v134
	v_cmp_gt_u32_e32 vcc, 16, v136
	v_sub_u32_e32 v135, v135, v133
	v_add_u32_e32 v135, 15, v135
	v_lshlrev_b32_e32 v135, 2, v135
	v_cndmask_b32_e32 v185, v137, v135, vcc
	v_add_u32_e32 v133, 16, v133
	v_add_u32_e32 v134, -8, v133
	v_max_i32_e32 v134, 0, v134
	v_min_i32_e32 v134, 48, v134
	v_add_u32_e32 v135, 0, v131
	v_sub_u32_e32 v136, v135, v134
	v_cmp_gt_u32_e32 vcc, 16, v136
	v_sub_u32_e32 v135, v135, v133
	v_add_u32_e32 v135, 15, v135
	v_lshlrev_b32_e32 v135, 2, v135
	v_cndmask_b32_e32 v186, v137, v135, vcc
	v_add_u32_e32 v135, 1, v131
	v_sub_u32_e32 v136, v135, v134
	v_cmp_gt_u32_e32 vcc, 16, v136
	v_sub_u32_e32 v135, v135, v133
	v_add_u32_e32 v135, 15, v135
	v_lshlrev_b32_e32 v135, 2, v135
	v_cndmask_b32_e32 v187, v137, v135, vcc
	v_add_u32_e32 v135, 2, v131
	v_sub_u32_e32 v136, v135, v134
	v_cmp_gt_u32_e32 vcc, 16, v136
	v_sub_u32_e32 v135, v135, v133
	v_add_u32_e32 v135, 15, v135
	v_lshlrev_b32_e32 v135, 2, v135
	v_cndmask_b32_e32 v188, v137, v135, vcc
	v_add_u32_e32 v135, 3, v131
	v_sub_u32_e32 v136, v135, v134
	v_cmp_gt_u32_e32 vcc, 16, v136
	v_sub_u32_e32 v135, v135, v133
	v_add_u32_e32 v135, 15, v135
	v_lshlrev_b32_e32 v135, 2, v135
	v_cndmask_b32_e32 v189, v137, v135, vcc
	v_add_u32_e32 v135, 4, v131
	v_sub_u32_e32 v136, v135, v134
	v_cmp_gt_u32_e32 vcc, 16, v136
	v_sub_u32_e32 v135, v135, v133
	v_add_u32_e32 v135, 15, v135
	v_lshlrev_b32_e32 v135, 2, v135
	v_cndmask_b32_e32 v190, v137, v135, vcc
	v_add_u32_e32 v135, 5, v131
	v_sub_u32_e32 v136, v135, v134
	v_cmp_gt_u32_e32 vcc, 16, v136
	v_sub_u32_e32 v135, v135, v133
	v_add_u32_e32 v135, 15, v135
	v_lshlrev_b32_e32 v135, 2, v135
	v_cndmask_b32_e32 v191, v137, v135, vcc
	v_add_u32_e32 v135, 6, v131
	v_sub_u32_e32 v136, v135, v134
	v_cmp_gt_u32_e32 vcc, 16, v136
	v_sub_u32_e32 v135, v135, v133
	v_add_u32_e32 v135, 15, v135
	v_lshlrev_b32_e32 v135, 2, v135
	v_cndmask_b32_e32 v192, v137, v135, vcc
	v_add_u32_e32 v135, 7, v131
	v_sub_u32_e32 v136, v135, v134
	v_cmp_gt_u32_e32 vcc, 16, v136
	v_sub_u32_e32 v135, v135, v133
	v_add_u32_e32 v135, 15, v135
	v_lshlrev_b32_e32 v135, 2, v135
	v_cndmask_b32_e32 v193, v137, v135, vcc
	v_add_u32_e32 v135, 32, v131
	v_sub_u32_e32 v136, v135, v134
	v_cmp_gt_u32_e32 vcc, 16, v136
	v_sub_u32_e32 v135, v135, v133
	v_add_u32_e32 v135, 15, v135
	v_lshlrev_b32_e32 v135, 2, v135
	v_cndmask_b32_e32 v194, v137, v135, vcc
	v_add_u32_e32 v135, 33, v131
	v_sub_u32_e32 v136, v135, v134
	v_cmp_gt_u32_e32 vcc, 16, v136
	v_sub_u32_e32 v135, v135, v133
	v_add_u32_e32 v135, 15, v135
	v_lshlrev_b32_e32 v135, 2, v135
	v_cndmask_b32_e32 v195, v137, v135, vcc
	v_add_u32_e32 v135, 34, v131
	v_sub_u32_e32 v136, v135, v134
	v_cmp_gt_u32_e32 vcc, 16, v136
	v_sub_u32_e32 v135, v135, v133
	v_add_u32_e32 v135, 15, v135
	v_lshlrev_b32_e32 v135, 2, v135
	v_cndmask_b32_e32 v213, v137, v135, vcc
	v_add_u32_e32 v135, 35, v131
	v_sub_u32_e32 v136, v135, v134
	v_cmp_gt_u32_e32 vcc, 16, v136
	v_sub_u32_e32 v135, v135, v133
	v_add_u32_e32 v135, 15, v135
	v_lshlrev_b32_e32 v135, 2, v135
	v_cndmask_b32_e32 v214, v137, v135, vcc
	v_add_u32_e32 v135, 36, v131
	v_sub_u32_e32 v136, v135, v134
	v_cmp_gt_u32_e32 vcc, 16, v136
	v_sub_u32_e32 v135, v135, v133
	v_add_u32_e32 v135, 15, v135
	v_lshlrev_b32_e32 v135, 2, v135
	v_cndmask_b32_e32 v215, v137, v135, vcc
	v_add_u32_e32 v135, 37, v131
	v_sub_u32_e32 v136, v135, v134
	v_cmp_gt_u32_e32 vcc, 16, v136
	v_sub_u32_e32 v135, v135, v133
	v_add_u32_e32 v135, 15, v135
	v_lshlrev_b32_e32 v135, 2, v135
	v_cndmask_b32_e32 v216, v137, v135, vcc
	v_add_u32_e32 v135, 38, v131
	v_sub_u32_e32 v136, v135, v134
	v_cmp_gt_u32_e32 vcc, 16, v136
	v_sub_u32_e32 v135, v135, v133
	v_add_u32_e32 v135, 15, v135
	v_lshlrev_b32_e32 v135, 2, v135
	v_cndmask_b32_e32 v217, v137, v135, vcc
	v_add_u32_e32 v135, 39, v131
	v_sub_u32_e32 v136, v135, v134
	v_cmp_gt_u32_e32 vcc, 16, v136
	v_sub_u32_e32 v135, v135, v133
	v_add_u32_e32 v135, 15, v135
	v_lshlrev_b32_e32 v135, 2, v135
	v_cndmask_b32_e32 v170, v137, v135, vcc
	s_waitcnt vmcnt(0)
	v_mul_f32_e32 v127, 0x3fb8aa3b, v127
	v_mul_f32_e32 v129, 0x3fb8aa3b, v129
	v_cmp_gt_u32_e32 vcc, 31, v124
	v_lshlrev_b32_e32 v130, 2, v196
	s_nop 1
	v_cndmask_b32_e32 v127, v205, v127, vcc
	v_cndmask_b32_e32 v129, v205, v129, vcc
	ds_write_b32 v130, v127 offset:51200
	ds_write_b32 v130, v129 offset:52224
	s_add_i32 s15, s12, 1
	s_cmp_ge_i32 s15, s24
	s_mov_b64 s[10:11], -1
	s_cbranch_scc0 .LBB0_244

.LBB0_253:
	s_andn2_b64 vcc, exec, s[10:11]
	s_cbranch_vccnz .LBB0_271
	v_readfirstlane_b32 s100, v218
	s_add_i32 s101, s21, s15
	s_nop 1
	s_sub_i32 s101, s101, s100
	s_add_i32 s101, s101, 6
	s_lshl_b32 s101, s101, 7
	v_add_u32_e32 v124, s101, v169
	ds_read_b32 v124, v124 offset:51200
	v_add_u32_e32 v125, s101, v171
	ds_read_b32 v125, v125 offset:51200
	v_add_u32_e32 v126, s101, v172
	ds_read_b32 v126, v126 offset:51200
	v_add_u32_e32 v127, s101, v173
	ds_read_b32 v127, v127 offset:51200
	v_add_u32_e32 v128, s101, v174
	ds_read_b32 v128, v128 offset:51200
	v_add_u32_e32 v129, s101, v175
	ds_read_b32 v129, v129 offset:51200
	v_add_u32_e32 v130, s101, v176
	ds_read_b32 v130, v130 offset:51200
	v_add_u32_e32 v131, s101, v177
	ds_read_b32 v131, v131 offset:51200
	v_add_u32_e32 v132, s101, v178
	ds_read_b32 v132, v132 offset:51200
	v_add_u32_e32 v133, s101, v179
	ds_read_b32 v133, v133 offset:51200
	v_add_u32_e32 v134, s101, v180
	ds_read_b32 v134, v134 offset:51200
	v_add_u32_e32 v135, s101, v181
	ds_read_b32 v135, v135 offset:51200
	v_add_u32_e32 v136, s101, v182
	ds_read_b32 v136, v136 offset:51200
	v_add_u32_e32 v137, s101, v183
	ds_read_b32 v137, v137 offset:51200
	v_add_u32_e32 v138, s101, v184
	ds_read_b32 v138, v138 offset:51200
	s_waitcnt lgkmcnt(7)
	v_add_f32_e32 v108, v108, v124
	v_add_f32_e32 v109, v109, v125
	v_add_f32_e32 v110, v110, v126
	v_add_f32_e32 v111, v111, v127
	v_add_f32_e32 v112, v112, v128
	v_add_f32_e32 v113, v113, v129
	v_add_f32_e32 v114, v114, v130
	v_add_f32_e32 v115, v115, v131
	v_add_u32_e32 v139, s101, v185
	ds_read_b32 v139, v139 offset:51200
	v_add_u32_e32 v240, s101, v186
	ds_read_b32 v240, v240 offset:51200
	v_add_u32_e32 v241, s101, v187
	ds_read_b32 v241, v241 offset:51200
	v_add_u32_e32 v242, s101, v188
	ds_read_b32 v242, v242 offset:51200
	v_add_u32_e32 v243, s101, v189
	ds_read_b32 v243, v243 offset:51200
	v_add_u32_e32 v244, s101, v190
	ds_read_b32 v244, v244 offset:51200
	v_add_u32_e32 v245, s101, v191
	ds_read_b32 v245, v245 offset:51200
	v_add_u32_e32 v246, s101, v192
	ds_read_b32 v246, v246 offset:51200
	s_waitcnt lgkmcnt(7)
	v_add_f32_e32 v120, v120, v132
	v_add_f32_e32 v121, v121, v133
	v_add_f32_e32 v122, v122, v134
	v_add_f32_e32 v123, v123, v135
	v_add_f32_e32 v116, v116, v136
	v_add_f32_e32 v117, v117, v137
	v_add_f32_e32 v118, v118, v138
	v_add_f32_e32 v119, v119, v139
	v_add_u32_e32 v247, s101, v193
	ds_read_b32 v247, v247 offset:51200
	v_add_u32_e32 v248, s101, v194
	ds_read_b32 v248, v248 offset:51200
	v_add_u32_e32 v249, s101, v195
	ds_read_b32 v249, v249 offset:51200
	v_add_u32_e32 v250, s101, v213
	ds_read_b32 v250, v250 offset:51200
	v_add_u32_e32 v251, s101, v214
	ds_read_b32 v251, v251 offset:51200
	v_add_u32_e32 v252, s101, v215
	ds_read_b32 v252, v252 offset:51200
	v_add_u32_e32 v253, s101, v216
	ds_read_b32 v253, v253 offset:51200
	v_add_u32_e32 v254, s101, v217
	ds_read_b32 v254, v254 offset:51200
	s_waitcnt lgkmcnt(7)
	v_add_f32_e32 v68, v68, v240
	v_add_f32_e32 v69, v69, v241
	v_add_f32_e32 v70, v70, v242
	v_add_f32_e32 v71, v71, v243
	v_add_f32_e32 v72, v72, v244
	v_add_f32_e32 v73, v73, v245
	v_add_f32_e32 v74, v74, v246
	v_add_f32_e32 v75, v75, v247
	v_add_u32_e32 v255, s101, v170
	ds_read_b32 v255, v255 offset:51200
	s_waitcnt lgkmcnt(0)
	v_add_f32_e32 v64, v64, v248
	v_add_f32_e32 v65, v65, v249
	v_add_f32_e32 v66, v66, v250
	v_add_f32_e32 v67, v67, v251
	v_add_f32_e32 v60, v60, v252
	v_add_f32_e32 v61, v61, v253
	v_add_f32_e32 v62, v62, v254
	v_add_f32_e32 v63, v63, v255
	v_mov_b32_e32 v136, v108
	v_mov_b32_e32 v134, v112
	v_mov_b32_e32 v142, v120
	v_mov_b32_e32 v140, v116
	v_mov_b32_e32 v126, v68
	v_mov_b32_e32 v124, v72
	v_mov_b32_e32 v132, v64
	v_mov_b32_e32 v130, v60

.LBB0_286:
	s_or_b64 exec, exec, s[58:59]
	s_add_i32 s2, s26, 1
	s_cmp_lg_u32 s26, 2
	s_cselect_b32 s26, s2, 0
	s_add_i32 s2, s27, 1
	s_cmp_lg_u32 s27, 2
	s_cselect_b32 s27, s2, 0
	s_cmp_lg_u32 s24, s15
	s_cbranch_scc0 .LBB0_288
	s_mov_b32 s12, s15
	s_add_i32 s15, s12, 1
	s_cmp_ge_i32 s15, s24
	s_mov_b64 s[10:11], -1
	s_cbranch_scc1 .LBB0_243
	s_branch .LBB0_244

	.amdhsa_kernel _Z4mega6Params
		.amdhsa_group_segment_fixed_size 0
		.amdhsa_private_segment_fixed_size 0
		.amdhsa_kernarg_size 472
		.amdhsa_user_sgpr_count 2
		.amdhsa_user_sgpr_dispatch_ptr 0
		.amdhsa_user_sgpr_queue_ptr 0
		.amdhsa_user_sgpr_kernarg_segment_ptr 1
		.amdhsa_user_sgpr_dispatch_id 0
		.amdhsa_user_sgpr_kernarg_preload_length 0
		.amdhsa_user_sgpr_kernarg_preload_offset 0
		.amdhsa_user_sgpr_private_segment_size 0
		.amdhsa_uses_dynamic_stack 0
		.amdhsa_enable_private_segment 0
		.amdhsa_system_sgpr_workgroup_id_x 1
		.amdhsa_system_sgpr_workgroup_id_y 0
		.amdhsa_system_sgpr_workgroup_id_z 0
		.amdhsa_system_sgpr_workgroup_info 0
		.amdhsa_system_vgpr_workitem_id 2
		.amdhsa_next_free_vgpr 256
		.amdhsa_next_free_sgpr 102
		.amdhsa_accum_offset 256
		.amdhsa_reserve_vcc 1
		.amdhsa_float_round_mode_32 0
		.amdhsa_float_round_mode_16_64 0
		.amdhsa_float_denorm_mode_32 3
		.amdhsa_float_denorm_mode_16_64 3
		.amdhsa_dx10_clamp 1
		.amdhsa_ieee_mode 1
		.amdhsa_fp16_overflow 0
		.amdhsa_tg_split 0
		.amdhsa_exception_fp_ieee_invalid_op 0
		.amdhsa_exception_fp_denorm_src 0
		.amdhsa_exception_fp_ieee_div_zero 0
		.amdhsa_exception_fp_ieee_overflow 0
		.amdhsa_exception_fp_ieee_underflow 0
		.amdhsa_exception_fp_ieee_inexact 0
		.amdhsa_exception_int_div_zero 0
	.end_amdhsa_kernel

amdhsa.kernels:
  - .agpr_count:     0
    .args:
      - .offset:         0
        .size:           216
        .value_kind:     by_value
      - .offset:         216
        .size:           4
        .value_kind:     hidden_block_count_x
      - .offset:         220
        .size:           4
        .value_kind:     hidden_block_count_y
      - .offset:         224
        .size:           4
        .value_kind:     hidden_block_count_z
      - .offset:         228
        .size:           2
        .value_kind:     hidden_group_size_x
      - .offset:         230
        .size:           2
        .value_kind:     hidden_group_size_y
      - .offset:         232
        .size:           2
        .value_kind:     hidden_group_size_z
      - .offset:         234
        .size:           2
        .value_kind:     hidden_remainder_x
      - .offset:         236
        .size:           2
        .value_kind:     hidden_remainder_y
      - .offset:         238
        .size:           2
        .value_kind:     hidden_remainder_z
      - .offset:         256
        .size:           8
        .value_kind:     hidden_global_offset_x
      - .offset:         264
        .size:           8
        .value_kind:     hidden_global_offset_y
      - .offset:         272
        .size:           8
        .value_kind:     hidden_global_offset_z
      - .offset:         280
        .size:           2
        .value_kind:     hidden_grid_dims
      - .offset:         304
        .size:           8
        .value_kind:     hidden_multigrid_sync_arg
      - .offset:         336
        .size:           4
        .value_kind:     hidden_dynamic_lds_size
    .group_segment_fixed_size: 0
    .kernarg_segment_align: 8
    .kernarg_segment_size: 472
    .language:       OpenCL C
    .language_version:
      - 2
      - 0
    .max_flat_workgroup_size: 256
    .name:           _Z4mega6Params
    .private_segment_fixed_size: 0
    .sgpr_count:     108
    .sgpr_spill_count: 249
    .symbol:         _Z4mega6Params.kd
    .uniform_work_group_size: 1
    .uses_dynamic_stack: false
    .vgpr_count:     256
    .vgpr_spill_count: 0
    .wavefront_size: 64
